# P0->P1 grid sync: cooperative-groups sync replaced by a MAGIC-word handshake (WG0 zeroes the barrier words write-through, publishes a magic) plus a flat counter barrier in device memory
# speedup vs baseline: 1.0144x; 1.0144x over previous
; __device__ __forceinline__ int tid_fresh() { int t = threadIdx.x; asm volatile("" : "+v"(t)); return t; }
; __global__ void __launch_bounds__(512) hybrid_step_fwd(Params P) {
;     ...
;     { const int t0_ = tid_fresh(); if (t0_ < 2) xst[t0_] = 0u; if (blockIdx.x == 0) for (int i = t0_; i < XCD_BAR_WORDS; i += 512) barw[i] = 0u; }
.LBB0_5:
	v_add_u32_e32 v8, -2, v8
	v_ashrrev_i32_e32 v11, 31, v5
	v_mov_b32_e32 v10, v5
	v_ashrrev_i32_e32 v13, 31, v4
	v_mov_b32_e32 v12, v4
	v_cmp_eq_u32_e32 vcc, 0, v8
	v_add_u32_e32 v5, 0x400, v5
	v_add_u32_e32 v4, 0x400, v4
	v_lshl_add_u64 v[12:13], v[12:13], 2, s[0:1]
	v_lshl_add_u64 v[10:11], v[10:11], 2, s[0:1]
	s_or_b64 s[8:9], vcc, s[8:9]
	global_store_dword v[12:13], v7, off sc0 sc1
	global_store_dword v[10:11], v7, off sc0 sc1
	s_andn2_b64 exec, exec, s[8:9]
	s_cbranch_execnz .LBB0_5
	s_or_b64 exec, exec, s[8:9]
	v_cmp_ne_u32_e32 vcc, v1, v6
	v_lshl_add_u32 v2, v6, 9, v2
	s_orn2_b64 s[8:9], vcc, exec

; __device__ __forceinline__ int tid_fresh() { int t = threadIdx.x; asm volatile("" : "+v"(t)); return t; }
; __global__ void __launch_bounds__(512) hybrid_step_fwd(Params P) {
;     ...
;     { const int t0_ = tid_fresh(); if (t0_ < 2) xst[t0_] = 0u; if (blockIdx.x == 0) for (int i = t0_; i < XCD_BAR_WORDS; i += 512) barw[i] = 0u; }
.LBB0_9:
	v_add_u32_e32 v1, 0x200, v1
	v_cmp_lt_i32_e32 vcc, s0, v1
	global_store_dword v[2:3], v4, off sc0 sc1
	s_or_b64 s[6:7], vcc, s[6:7]
	v_lshl_add_u64 v[2:3], v[2:3], 0, s[8:9]
	s_andn2_b64 exec, exec, s[6:7]
	s_cbranch_execnz .LBB0_9
.LBB0_10:
	v_writelane_b32 v252, s10, 4
	s_nop 1
	v_writelane_b32 v252, s11, 5
	v_writelane_b32 v252, s12, 6
	s_nop 1
	v_writelane_b32 v252, s13, 7
	v_writelane_b32 v252, s14, 8
	v_writelane_b32 v252, s15, 9
	s_or_b64 exec, exec, s[4:5]
	s_andn2_b64 vcc, exec, s[18:19]
	s_cbranch_vccnz .Lcgm_early_done
	s_waitcnt vmcnt(0)
	s_barrier
	v_cmp_eq_u32_e32 vcc, 0, v251
	s_and_saveexec_b64 s[4:5], vcc
	s_cbranch_execz .Lcgm_early_x
	v_readlane_b32 s6, v252, 2
	v_readlane_b32 s7, v252, 3
	v_mov_b32_e32 v3, 0
	v_mov_b32_e32 v4, 0x5eedb10c
	s_nop 3
	global_store_dword v3, v4, s[6:7] offset:4 sc0 sc1

; #define LAS __attribute__((address_space(3)))
; __device__ __forceinline__ int tid_fresh() { int t = threadIdx.x; asm volatile("" : "+v"(t)); return t; }
; __device__ __forceinline__ void phase0(const Params& P, LAS unsigned char* lds, int G) {
;     const int tid = tid_fresh(), lane = tid & 63, wave = tid >> 6;
;     const int gw = blockIdx.x * 8 + wave, NGW = G * 8;
;     unsigned char* ws = P.ws;
;     const float* w_in = P.in[12];
;     const float* norm_mix = P.in[11];
;     LAS float* wg = (LAS float*)(lds + 72 * 1024);
;     for (int idx = tid; idx < 8192; idx += 512) { const int j = idx >> 10, k = idx & 1023; wg[idx] = w_in[(size_t)k * 8456 + 6400 + j] * norm_mix[k]; }
;     __syncthreads();
;     {
;         const float* xp = P.in[0]; const float* xs = P.in[1];
;         bf16* XN = (bf16*)(ws + WS_XN); float* GT = (float*)(ws + WS_GATES);
;         const float* b_ig = P.in[15]; const float* b_fg = P.in[16];
;         for (int row = gw; row < MT; row += NGW) {
.Lcgm_early_done:
	s_mov_b32 s0, 1
	s_cmp_lt_i32 s0, 1
	v_mbcnt_lo_u32_b32 v232, -1, 0
	s_cbranch_scc1 .LBB0_109
	v_readlane_b32 s6, v252, 4
	v_readlane_b32 s7, v252, 5
	s_load_dwordx4 s[8:11], s[6:7], 0xf0
	v_readlane_b32 s5, v252, 0
	s_lshl_b32 s1, s5, 3
	s_load_dwordx8 s[20:27], s[6:7], 0x48
	s_load_dwordx4 s[28:31], s[6:7], 0x0
	s_load_dwordx4 s[36:39], s[6:7], 0x78
	s_waitcnt lgkmcnt(0)
	s_lshl_b32 s34, s10, 3
	s_add_u32 s40, s8, 0x2800000
	s_addc_u32 s41, s9, 0
	s_add_u32 s42, s8, 0x39c3500
	s_addc_u32 s43, s9, 0
	s_add_u32 s44, s8, 0x35a3500
	s_addc_u32 s45, s9, 0
	s_add_u32 s46, s8, 0x36a7500
	s_addc_u32 s47, s9, 0
	s_add_u32 s48, s8, 0x37ab500
	s_addc_u32 s49, s9, 0
	s_add_u32 s50, s8, 0x28c0500
	s_addc_u32 s51, s9, 0
	s_lshl_b32 s33, s5, 9
	s_lshl_b32 s78, s10, 9
	s_add_u32 s52, s8, 0x2880400
	s_addc_u32 s53, s9, 0
	s_cmp_lg_u64 s[24:25], 0
	s_cselect_b64 s[54:55], -1, 0
	s_ashr_i32 s35, s34, 31
	s_lshl_b64 s[56:57], s[34:35], 12
	v_lshrrev_b32_e32 v1, 20, v0
	v_lshrrev_b32_e32 v0, 10, v0
	s_add_u32 s58, s8, 0x36a3500
	v_or_b32_e32 v0, v0, v1
	s_movk_i32 s4, 0x3ff
	s_addc_u32 s59, s9, 0
	s_lshl_b32 s80, s5, 12
	s_lshl_b32 s81, s10, 12
	s_lshl_b32 s82, s5, 10
	s_lshl_b32 s83, s10, 10
	v_and_or_b32 v0, v0, s4, v251
	s_add_u32 s60, s24, 56
	s_mov_b32 s62, 0x6dc9c883
	s_mov_b32 s79, 0
	s_addc_u32 s61, s25, 0
	s_add_i32 s84, 0, 0x13800
	s_mov_b32 s85, 0x8420
	s_movk_i32 s86, 0x6000
	v_mov_b32_e32 v145, 0
	s_movk_i32 s87, 0x3fff
	v_mov_b32_e32 v170, 0x358637bd
	v_mov_b32_e32 v171, 0x260
	v_mov_b32_e32 v172, 0x3eaaaaab
	s_mov_b32 s63, 0x3fc45f30
	s_mov_b32 s88, 0x3e0f83e1
	v_mbcnt_hi_u32_b32 v173, -1, v232
	v_mov_b32_e32 v174, 13
	v_mov_b32_e32 v175, 0x41b17218
	v_mov_b64_e32 v[146:147], 0x100000
	v_mov_b32_e32 v176, 0x372d07a7
	v_mov_b32_e32 v177, 0x385f10c4
	v_mov_b32_e32 v180, 0x4000
	s_movk_i32 s89, 0xc7
	s_movk_i32 s90, 0x107f
	v_cmp_eq_u32_e64 s[14:15], 0, v0
	s_mov_b64 s[64:65], 0x6400
	s_mov_b64 s[66:67], 0x800
	s_branch .LBB0_14

; __global__ void __launch_bounds__(512) hybrid_step_fwd(Params P) {
;     ...
;         grid.sync();
.LBB0_100:
	s_or_b64 exec, exec, s[6:7]
	s_waitcnt vmcnt(0) lgkmcnt(0)
	s_barrier
	s_and_saveexec_b64 s[4:5], s[14:15]
	s_cbranch_execz .LBB0_13
	buffer_wbl2 sc1
	s_load_dword s101, s[2:3], 0x0
	v_readlane_b32 s6, v252, 2
	v_readlane_b32 s7, v252, 3
	s_movk_i32 s98, 0x2000
	s_mov_b32 s100, 0x5eedb10c
	s_waitcnt vmcnt(0) lgkmcnt(0)
.Lcgm_magic:
	global_load_dword v1, v145, s[6:7] offset:4 sc1
	s_waitcnt vmcnt(0)
	v_readfirstlane_b32 s99, v1
	s_nop 3
	s_cmp_eq_u32 s99, s100
	s_cbranch_scc1 .Lcgm_magic_done
	s_sleep 1
	s_sub_u32 s98, s98, 1
	s_cmp_lg_u32 s98, 0
	s_cbranch_scc1 .Lcgm_magic
.Lcgm_magic_done:
	v_mov_b32_e32 v1, 1
	global_atomic_add v145, v1, s[6:7]
	s_movk_i32 s98, 0x2000
.Lcgm_cnt:
	global_load_dword v1, v145, s[6:7] sc1
	s_waitcnt vmcnt(0)
	v_readfirstlane_b32 s99, v1
	s_nop 3
	s_cmp_ge_u32 s99, s101
	s_cbranch_scc1 .Lcgm_cnt_done
	s_sleep 1
	s_sub_u32 s98, s98, 1
	s_cmp_lg_u32 s98, 0
	s_cbranch_scc1 .Lcgm_cnt
.Lcgm_cnt_done:
	buffer_inv sc1
	s_waitcnt vmcnt(0)
	s_branch .LBB0_13
